# v38 plus non-temporal hint on the P0 rmsnorm x row loads
# speedup vs baseline: 1.0068x; 1.0018x over previous
; __device__ __forceinline__ unsigned cvt_pk_bf16(float lo, float hi) { f32x2 v = {lo, hi}; bf16x2_t b = __builtin_convertvector(v, bf16x2_t); return __builtin_bit_cast(unsigned, b); }
; #define KIN(i) (*(const float* const __attribute__((address_space(4)))*)(kp + 8 * (i)))
; __device__ __forceinline__ void rms_row_to_bf16(const float* xrow, const float* g, bf16* orow, int lane) {
;     const f32x4* xr = (const f32x4*)xrow + lane; const f32x4* gr = (const f32x4*)g + lane;
;     f32x4 v[8]; float s = 0.f;
; #pragma unroll
;     for (int j = 0; j < 8; ++j) { v[j] = xr[64 * j]; s += (v[j].x * v[j].x + v[j].y * v[j].y) + (v[j].z * v[j].z + v[j].w * v[j].w); }
;     const float r = 1.0f / sqrtf(wave_sum(s) * (1.0f / DM) + EPS);
;     u32x2* o8 = (u32x2*)orow + lane;
; #pragma unroll
;     for (int j = 0; j < 8; ++j) { const f32x4 gg = gr[64 * j]; u32x2 w; w.x = cvt_pk_bf16(v[j].x * r * gg.x, v[j].y * r * gg.y); w.y = cvt_pk_bf16(v[j].z * r * gg.z, v[j].w * r * gg.w); o8[64 * j] = w; }
; }
; __global__ void __launch_bounds__(512, 2) fwd_megakernel(Args a) {
;     ...
;             for (int m = gw; m < MTOK; m += NGW) rms_row_to_bf16(KIN(0) + (size_t)m * DM, KIN(2), XN + (size_t)m * DM, lane);
.LBB0_503:
	global_load_dwordx4 v[64:67], v[38:39], off
	global_load_dwordx4 v[68:71], v[38:39], off offset:1024
	global_load_dwordx4 v[72:75], v[38:39], off offset:2048
	global_load_dwordx4 v[76:79], v[38:39], off offset:3072
	global_load_dwordx4 v[80:83], v[40:41], off
	global_load_dwordx4 v[84:87], v[42:43], off
	global_load_dwordx4 v[88:91], v[44:45], off
	global_load_dwordx4 v[92:95], v[46:47], off
	v_add_co_u32_e32 v2, vcc, 0xfffff000, v50
	s_nop 1
	v_addc_co_u32_e32 v3, vcc, -1, v51, vcc
	global_load_dwordx4 v[116:119], v[2:3], off offset:-3072 nt
	global_load_dwordx4 v[120:123], v[2:3], off offset:-2048 nt
	global_load_dwordx4 v[124:127], v[2:3], off offset:-1024 nt
	global_load_dwordx4 v[128:131], v[2:3], off nt
	global_load_dwordx4 v[132:135], v[50:51], off offset:-3072 nt
	global_load_dwordx4 v[136:139], v[50:51], off offset:-2048 nt
	global_load_dwordx4 v[140:143], v[50:51], off offset:-1024 nt
	global_load_dwordx4 v[144:147], v[50:51], off nt
	v_lshl_add_u64 v[50:51], v[50:51], 0, s[86:87]
.Lrms_loop:
	s_add_i32 s88, s88, s66
	s_cmpk_gt_i32 s88, 0x7fff
	s_cbranch_scc1 .Lrms_last_a
	v_add_co_u32_e32 v2, vcc, 0xfffff000, v50
	s_nop 1
	v_addc_co_u32_e32 v3, vcc, -1, v51, vcc
	global_load_dwordx4 v[148:151], v[2:3], off offset:-3072 nt
	global_load_dwordx4 v[152:155], v[2:3], off offset:-2048 nt
	global_load_dwordx4 v[156:159], v[2:3], off offset:-1024 nt
	global_load_dwordx4 v[160:163], v[2:3], off nt
	global_load_dwordx4 v[164:167], v[50:51], off offset:-3072 nt
	global_load_dwordx4 v[168:171], v[50:51], off offset:-2048 nt
	global_load_dwordx4 v[172:175], v[50:51], off offset:-1024 nt
	global_load_dwordx4 v[176:179], v[50:51], off nt
	v_lshl_add_u64 v[50:51], v[50:51], 0, s[86:87]
	s_waitcnt vmcnt(8)
	v_pk_mul_f32 v[4:5], v[116:117], v[116:117]
	v_pk_mul_f32 v[6:7], v[118:119], v[118:119]
	v_pk_fma_f32 v[4:5], v[120:121], v[120:121], v[4:5]
	v_pk_fma_f32 v[6:7], v[122:123], v[122:123], v[6:7]
	v_pk_fma_f32 v[4:5], v[124:125], v[124:125], v[4:5]
	v_pk_fma_f32 v[6:7], v[126:127], v[126:127], v[6:7]
	v_pk_fma_f32 v[4:5], v[128:129], v[128:129], v[4:5]
	v_pk_fma_f32 v[6:7], v[130:131], v[130:131], v[6:7]
	v_pk_fma_f32 v[4:5], v[132:133], v[132:133], v[4:5]
	v_pk_fma_f32 v[6:7], v[134:135], v[134:135], v[6:7]
	v_pk_fma_f32 v[4:5], v[136:137], v[136:137], v[4:5]
	v_pk_fma_f32 v[6:7], v[138:139], v[138:139], v[6:7]
	v_pk_fma_f32 v[4:5], v[140:141], v[140:141], v[4:5]
	v_pk_fma_f32 v[6:7], v[142:143], v[142:143], v[6:7]
	v_pk_fma_f32 v[4:5], v[144:145], v[144:145], v[4:5]
	v_pk_fma_f32 v[6:7], v[146:147], v[146:147], v[6:7]
	v_pk_add_f32 v[4:5], v[4:5], v[6:7]
	s_nop 0
	v_add_f32_e32 v34, v4, v5
	ds_bpermute_b32 v35, v1, v34
	s_waitcnt lgkmcnt(0)
	v_add_f32_e32 v34, v34, v35
	ds_bpermute_b32 v35, v53, v34
	s_waitcnt lgkmcnt(0)
	v_add_f32_e32 v34, v34, v35
	ds_bpermute_b32 v35, v54, v34
	s_waitcnt lgkmcnt(0)
	v_add_f32_e32 v34, v34, v35
	ds_bpermute_b32 v35, v55, v34
	s_waitcnt lgkmcnt(0)
	v_add_f32_e32 v34, v34, v35
	ds_bpermute_b32 v35, v56, v34
	s_waitcnt lgkmcnt(0)
	v_add_f32_e32 v34, v34, v35
	ds_bpermute_b32 v35, v57, v34
	s_waitcnt lgkmcnt(0)
	v_add_f32_e32 v34, v34, v35
	v_fmamk_f32 v34, v34, 0x3a000000, v214
	v_cmp_gt_f32_e32 vcc, s33, v34
	v_mul_f32_e32 v35, 0x4f800000, v34
	s_nop 0
	v_cndmask_b32_e32 v34, v34, v35, vcc
	v_sqrt_f32_e32 v35, v34
	s_nop 0
	v_add_u32_e32 v36, -1, v35
	v_fma_f32 v37, -v36, v35, v34
	v_cmp_ge_f32_e64 s[4:5], 0, v37
	v_add_u32_e32 v37, 1, v35
	s_nop 0
	v_cndmask_b32_e64 v36, v35, v36, s[4:5]
	v_fma_f32 v35, -v37, v35, v34
	v_cmp_lt_f32_e64 s[4:5], 0, v35
	s_nop 1
	v_cndmask_b32_e64 v35, v36, v37, s[4:5]
	v_mul_f32_e32 v36, 0x37800000, v35
	v_cndmask_b32_e32 v35, v35, v36, vcc
	v_cmp_class_f32_e32 vcc, v34, v215
	s_nop 1
	v_cndmask_b32_e32 v34, v35, v34, vcc
	v_div_scale_f32 v35, s[4:5], v34, v34, 1.0
	v_rcp_f32_e32 v36, v35
	s_nop 0
	v_fma_f32 v37, -v35, v36, 1.0
	v_fmac_f32_e32 v36, v37, v36
	v_div_scale_f32 v37, vcc, 1.0, v34, 1.0
	v_mul_f32_e32 v52, v37, v36
	v_fma_f32 v58, -v35, v52, v37
	v_fmac_f32_e32 v52, v58, v36
	v_fma_f32 v35, -v35, v52, v37
	v_div_fmas_f32 v35, v35, v36, v52
	v_div_fixup_f32 v52, v35, v34, 1.0
	v_pk_mul_f32 v[2:3], v[116:117], v[52:53] op_sel_hi:[1,0]
	v_pk_mul_f32 v[4:5], v[118:119], v[52:53] op_sel_hi:[1,0]
	v_pk_mul_f32 v[2:3], v[64:65], v[2:3]
	v_pk_mul_f32 v[4:5], v[66:67], v[4:5]
	v_cvt_pk_bf16_f32 v8, v2, v3
	v_cvt_pk_bf16_f32 v9, v4, v5
	global_store_dwordx2 v[48:49], v[8:9], off offset:-3584
	v_pk_mul_f32 v[2:3], v[120:121], v[52:53] op_sel_hi:[1,0]
	v_pk_mul_f32 v[4:5], v[122:123], v[52:53] op_sel_hi:[1,0]
	v_pk_mul_f32 v[2:3], v[68:69], v[2:3]
	v_pk_mul_f32 v[4:5], v[70:71], v[4:5]
	v_cvt_pk_bf16_f32 v10, v2, v3
	v_cvt_pk_bf16_f32 v11, v4, v5
	global_store_dwordx2 v[48:49], v[10:11], off offset:-3072
	v_pk_mul_f32 v[2:3], v[124:125], v[52:53] op_sel_hi:[1,0]
	v_pk_mul_f32 v[4:5], v[126:127], v[52:53] op_sel_hi:[1,0]
	v_pk_mul_f32 v[2:3], v[72:73], v[2:3]
	v_pk_mul_f32 v[4:5], v[74:75], v[4:5]
	v_cvt_pk_bf16_f32 v12, v2, v3
	v_cvt_pk_bf16_f32 v13, v4, v5
	global_store_dwordx2 v[48:49], v[12:13], off offset:-2560
	v_pk_mul_f32 v[2:3], v[128:129], v[52:53] op_sel_hi:[1,0]
	v_pk_mul_f32 v[4:5], v[130:131], v[52:53] op_sel_hi:[1,0]
	v_pk_mul_f32 v[2:3], v[76:77], v[2:3]
	v_pk_mul_f32 v[4:5], v[78:79], v[4:5]
	v_cvt_pk_bf16_f32 v14, v2, v3
	v_cvt_pk_bf16_f32 v15, v4, v5
	global_store_dwordx2 v[48:49], v[14:15], off offset:-2048
	v_pk_mul_f32 v[2:3], v[132:133], v[52:53] op_sel_hi:[1,0]
	v_pk_mul_f32 v[4:5], v[134:135], v[52:53] op_sel_hi:[1,0]
	v_pk_mul_f32 v[2:3], v[80:81], v[2:3]
	v_pk_mul_f32 v[4:5], v[82:83], v[4:5]
	v_cvt_pk_bf16_f32 v16, v2, v3
	v_cvt_pk_bf16_f32 v17, v4, v5
	global_store_dwordx2 v[48:49], v[16:17], off offset:-1536
	v_pk_mul_f32 v[2:3], v[136:137], v[52:53] op_sel_hi:[1,0]
	v_pk_mul_f32 v[4:5], v[138:139], v[52:53] op_sel_hi:[1,0]
	v_pk_mul_f32 v[2:3], v[84:85], v[2:3]
	v_pk_mul_f32 v[4:5], v[86:87], v[4:5]
	v_cvt_pk_bf16_f32 v18, v2, v3
	v_cvt_pk_bf16_f32 v19, v4, v5
	global_store_dwordx2 v[48:49], v[18:19], off offset:-1024
	v_pk_mul_f32 v[2:3], v[140:141], v[52:53] op_sel_hi:[1,0]
	v_pk_mul_f32 v[4:5], v[142:143], v[52:53] op_sel_hi:[1,0]
	v_pk_mul_f32 v[2:3], v[88:89], v[2:3]
	v_pk_mul_f32 v[4:5], v[90:91], v[4:5]
	v_cvt_pk_bf16_f32 v20, v2, v3
	v_cvt_pk_bf16_f32 v21, v4, v5
	global_store_dwordx2 v[48:49], v[20:21], off offset:-512
	v_pk_mul_f32 v[2:3], v[144:145], v[52:53] op_sel_hi:[1,0]
	v_pk_mul_f32 v[4:5], v[146:147], v[52:53] op_sel_hi:[1,0]
	v_pk_mul_f32 v[2:3], v[92:93], v[2:3]
	v_pk_mul_f32 v[4:5], v[94:95], v[4:5]
	v_cvt_pk_bf16_f32 v22, v2, v3
	v_cvt_pk_bf16_f32 v23, v4, v5
	global_store_dwordx2 v[48:49], v[22:23], off
	v_lshl_add_u64 v[48:49], v[48:49], 0, s[6:7]
	s_add_i32 s88, s88, s66
	s_cmpk_gt_i32 s88, 0x7fff
	s_cbranch_scc1 .Lrms_last_b
; __device__ __forceinline__ unsigned cvt_pk_bf16(float lo, float hi) { f32x2 v = {lo, hi}; bf16x2_t b = __builtin_convertvector(v, bf16x2_t); return __builtin_bit_cast(unsigned, b); }
; __device__ __forceinline__ void rms_row_to_bf16(const float* xrow, const float* g, bf16* orow, int lane) {
;     const f32x4* xr = (const f32x4*)xrow + lane; const f32x4* gr = (const f32x4*)g + lane;
;     f32x4 v[8]; float s = 0.f;
; #pragma unroll
;     for (int j = 0; j < 8; ++j) { v[j] = xr[64 * j]; s += (v[j].x * v[j].x + v[j].y * v[j].y) + (v[j].z * v[j].z + v[j].w * v[j].w); }
;     const float r = 1.0f / sqrtf(wave_sum(s) * (1.0f / DM) + EPS);
;     u32x2* o8 = (u32x2*)orow + lane;
; #pragma unroll
;     for (int j = 0; j < 8; ++j) { const f32x4 gg = gr[64 * j]; u32x2 w; w.x = cvt_pk_bf16(v[j].x * r * gg.x, v[j].y * r * gg.y); w.y = cvt_pk_bf16(v[j].z * r * gg.z, v[j].w * r * gg.w); o8[64 * j] = w; }
; }
	v_add_co_u32_e32 v2, vcc, 0xfffff000, v50
	s_nop 1
	v_addc_co_u32_e32 v3, vcc, -1, v51, vcc
	global_load_dwordx4 v[116:119], v[2:3], off offset:-3072 nt
	global_load_dwordx4 v[120:123], v[2:3], off offset:-2048 nt
	global_load_dwordx4 v[124:127], v[2:3], off offset:-1024 nt
	global_load_dwordx4 v[128:131], v[2:3], off nt
	global_load_dwordx4 v[132:135], v[50:51], off offset:-3072 nt
	global_load_dwordx4 v[136:139], v[50:51], off offset:-2048 nt
	global_load_dwordx4 v[140:143], v[50:51], off offset:-1024 nt
	global_load_dwordx4 v[144:147], v[50:51], off nt
	v_lshl_add_u64 v[50:51], v[50:51], 0, s[86:87]
	s_waitcnt vmcnt(8)
	v_pk_mul_f32 v[4:5], v[148:149], v[148:149]
	v_pk_mul_f32 v[6:7], v[150:151], v[150:151]
	v_pk_fma_f32 v[4:5], v[152:153], v[152:153], v[4:5]
	v_pk_fma_f32 v[6:7], v[154:155], v[154:155], v[6:7]
	v_pk_fma_f32 v[4:5], v[156:157], v[156:157], v[4:5]
	v_pk_fma_f32 v[6:7], v[158:159], v[158:159], v[6:7]
	v_pk_fma_f32 v[4:5], v[160:161], v[160:161], v[4:5]
	v_pk_fma_f32 v[6:7], v[162:163], v[162:163], v[6:7]
	v_pk_fma_f32 v[4:5], v[164:165], v[164:165], v[4:5]
	v_pk_fma_f32 v[6:7], v[166:167], v[166:167], v[6:7]
	v_pk_fma_f32 v[4:5], v[168:169], v[168:169], v[4:5]
	v_pk_fma_f32 v[6:7], v[170:171], v[170:171], v[6:7]
	v_pk_fma_f32 v[4:5], v[172:173], v[172:173], v[4:5]
	v_pk_fma_f32 v[6:7], v[174:175], v[174:175], v[6:7]
	v_pk_fma_f32 v[4:5], v[176:177], v[176:177], v[4:5]
	v_pk_fma_f32 v[6:7], v[178:179], v[178:179], v[6:7]
	v_pk_add_f32 v[4:5], v[4:5], v[6:7]
	s_nop 0
	v_add_f32_e32 v34, v4, v5
	ds_bpermute_b32 v35, v1, v34
	s_waitcnt lgkmcnt(0)
	v_add_f32_e32 v34, v34, v35
	ds_bpermute_b32 v35, v53, v34
	s_waitcnt lgkmcnt(0)
	v_add_f32_e32 v34, v34, v35
	ds_bpermute_b32 v35, v54, v34
	s_waitcnt lgkmcnt(0)
	v_add_f32_e32 v34, v34, v35
	ds_bpermute_b32 v35, v55, v34
	s_waitcnt lgkmcnt(0)
	v_add_f32_e32 v34, v34, v35
	ds_bpermute_b32 v35, v56, v34
	s_waitcnt lgkmcnt(0)
	v_add_f32_e32 v34, v34, v35
	ds_bpermute_b32 v35, v57, v34
	s_waitcnt lgkmcnt(0)
	v_add_f32_e32 v34, v34, v35
	v_fmamk_f32 v34, v34, 0x3a000000, v214
	v_cmp_gt_f32_e32 vcc, s33, v34
	v_mul_f32_e32 v35, 0x4f800000, v34
	s_nop 0
	v_cndmask_b32_e32 v34, v34, v35, vcc
	v_sqrt_f32_e32 v35, v34
	s_nop 0
	v_add_u32_e32 v36, -1, v35
	v_fma_f32 v37, -v36, v35, v34
	v_cmp_ge_f32_e64 s[4:5], 0, v37
	v_add_u32_e32 v37, 1, v35
	s_nop 0
	v_cndmask_b32_e64 v36, v35, v36, s[4:5]
	v_fma_f32 v35, -v37, v35, v34
	v_cmp_lt_f32_e64 s[4:5], 0, v35
	s_nop 1
	v_cndmask_b32_e64 v35, v36, v37, s[4:5]
	v_mul_f32_e32 v36, 0x37800000, v35
	v_cndmask_b32_e32 v35, v35, v36, vcc
	v_cmp_class_f32_e32 vcc, v34, v215
	s_nop 1
	v_cndmask_b32_e32 v34, v35, v34, vcc
	v_div_scale_f32 v35, s[4:5], v34, v34, 1.0
	v_rcp_f32_e32 v36, v35
	s_nop 0
	v_fma_f32 v37, -v35, v36, 1.0
	v_fmac_f32_e32 v36, v37, v36
	v_div_scale_f32 v37, vcc, 1.0, v34, 1.0
	v_mul_f32_e32 v52, v37, v36
	v_fma_f32 v58, -v35, v52, v37
	v_fmac_f32_e32 v52, v58, v36
	v_fma_f32 v35, -v35, v52, v37
	v_div_fmas_f32 v35, v35, v36, v52
	v_div_fixup_f32 v52, v35, v34, 1.0
	v_pk_mul_f32 v[2:3], v[148:149], v[52:53] op_sel_hi:[1,0]
	v_pk_mul_f32 v[4:5], v[150:151], v[52:53] op_sel_hi:[1,0]
	v_pk_mul_f32 v[2:3], v[64:65], v[2:3]
	v_pk_mul_f32 v[4:5], v[66:67], v[4:5]
	v_cvt_pk_bf16_f32 v8, v2, v3
	v_cvt_pk_bf16_f32 v9, v4, v5
	global_store_dwordx2 v[48:49], v[8:9], off offset:-3584
	v_pk_mul_f32 v[2:3], v[152:153], v[52:53] op_sel_hi:[1,0]
	v_pk_mul_f32 v[4:5], v[154:155], v[52:53] op_sel_hi:[1,0]
	v_pk_mul_f32 v[2:3], v[68:69], v[2:3]
	v_pk_mul_f32 v[4:5], v[70:71], v[4:5]
	v_cvt_pk_bf16_f32 v10, v2, v3
	v_cvt_pk_bf16_f32 v11, v4, v5
	global_store_dwordx2 v[48:49], v[10:11], off offset:-3072
	v_pk_mul_f32 v[2:3], v[156:157], v[52:53] op_sel_hi:[1,0]
	v_pk_mul_f32 v[4:5], v[158:159], v[52:53] op_sel_hi:[1,0]
	v_pk_mul_f32 v[2:3], v[72:73], v[2:3]
	v_pk_mul_f32 v[4:5], v[74:75], v[4:5]
	v_cvt_pk_bf16_f32 v12, v2, v3
	v_cvt_pk_bf16_f32 v13, v4, v5
	global_store_dwordx2 v[48:49], v[12:13], off offset:-2560
	v_pk_mul_f32 v[2:3], v[160:161], v[52:53] op_sel_hi:[1,0]
	v_pk_mul_f32 v[4:5], v[162:163], v[52:53] op_sel_hi:[1,0]
	v_pk_mul_f32 v[2:3], v[76:77], v[2:3]
	v_pk_mul_f32 v[4:5], v[78:79], v[4:5]
	v_cvt_pk_bf16_f32 v14, v2, v3
	v_cvt_pk_bf16_f32 v15, v4, v5
	global_store_dwordx2 v[48:49], v[14:15], off offset:-2048
	v_pk_mul_f32 v[2:3], v[164:165], v[52:53] op_sel_hi:[1,0]
	v_pk_mul_f32 v[4:5], v[166:167], v[52:53] op_sel_hi:[1,0]
	v_pk_mul_f32 v[2:3], v[80:81], v[2:3]
	v_pk_mul_f32 v[4:5], v[82:83], v[4:5]
	v_cvt_pk_bf16_f32 v16, v2, v3
	v_cvt_pk_bf16_f32 v17, v4, v5
	global_store_dwordx2 v[48:49], v[16:17], off offset:-1536
	v_pk_mul_f32 v[2:3], v[168:169], v[52:53] op_sel_hi:[1,0]
	v_pk_mul_f32 v[4:5], v[170:171], v[52:53] op_sel_hi:[1,0]
	v_pk_mul_f32 v[2:3], v[84:85], v[2:3]
	v_pk_mul_f32 v[4:5], v[86:87], v[4:5]
	v_cvt_pk_bf16_f32 v18, v2, v3
	v_cvt_pk_bf16_f32 v19, v4, v5
	global_store_dwordx2 v[48:49], v[18:19], off offset:-1024
	v_pk_mul_f32 v[2:3], v[172:173], v[52:53] op_sel_hi:[1,0]
	v_pk_mul_f32 v[4:5], v[174:175], v[52:53] op_sel_hi:[1,0]
	v_pk_mul_f32 v[2:3], v[88:89], v[2:3]
	v_pk_mul_f32 v[4:5], v[90:91], v[4:5]
	v_cvt_pk_bf16_f32 v20, v2, v3
	v_cvt_pk_bf16_f32 v21, v4, v5
	global_store_dwordx2 v[48:49], v[20:21], off offset:-512
	v_pk_mul_f32 v[2:3], v[176:177], v[52:53] op_sel_hi:[1,0]
	v_pk_mul_f32 v[4:5], v[178:179], v[52:53] op_sel_hi:[1,0]
	v_pk_mul_f32 v[2:3], v[92:93], v[2:3]
	v_pk_mul_f32 v[4:5], v[94:95], v[4:5]
	v_cvt_pk_bf16_f32 v22, v2, v3
	v_cvt_pk_bf16_f32 v23, v4, v5
	global_store_dwordx2 v[48:49], v[22:23], off
	v_lshl_add_u64 v[48:49], v[48:49], 0, s[6:7]
	s_branch .Lrms_loop
